# MoBA steady loop: block mask folded into QK accumulator init v[48:63]; 32 v_cndmask copies per tile removed, max/exp/rescale read accumulators directly
# baseline (speedup 1.0000x reference)
; #define WAIT_BAR(N) asm volatile("s_waitcnt vmcnt(" #N ") lgkmcnt(0)\n\ts_barrier":::"memory")
;   #define DMA_K(t,slot) glds16(ksrc+(long)(t)*KVBLK*DM,(unsigned)__builtin_amdgcn_readfirstlane(kdst+(slot)))
;   #define DMA_V(t,slot) glds16(vsrc+(long)(t)*KVBLK*DM,(unsigned)__builtin_amdgcn_readfirstlane(vdst+(slot)))
;   #define CMASK(P0,P1,t) do{int jb_=(t)-(NT-4); if(jb_>=0)cmask(P0,P1,jb_,qrel,hi);}while(0)
;   #define ROT() do{sl_prev=sl_cur;sl_cur=sl_next;sl_next=(sl_next==(NSLOT-1)*SLOTB)?0:sl_next+SLOTB;}while(0)
;   #define CMASK(P0,P1,t) do{}while(0)
;   #define CMASK(P0,P1,t) do{int jb_=(t)-(NT-4); if(jb_>=0)cmask(P0,P1,jb_,qrel,hi);}while(0)
; template<int THRL,int MODE,int DM,bool DRY=false> __device__ __forceinline__ void attn_unit(int b,int h,int qb,const bf16*Q,const bf16*__restrict__ K,const bf16*__restrict__ V,bf16*O,const bf16*__restrict__ Z,const float*__restrict__ XP,const int*__restrict__ TS,volatile unsigned*lw,unsigned nxt,cha ...
;     ...
;   qkt(pA0,pA1,Kbase,qr,NEGM,r32,hi);asm volatile("s_nop 15\n\ts_nop 7":"+v"(pA0),"+v"(pA1));XMASK(pA0,pA1,0);CMASK(pA0,pA1,0);
;   START(pA0,pA1);
;   _Pragma("unroll") for(int r=0;r<16;++r)pA1[r]=__builtin_amdgcn_exp2f(pA1[r]);
;   WAIT_BAR(0);
;   DMA_K(3,0);DMA_V(1,SLOTB);
;   ROT();
;   kload8(kf,kp0+sl_cur);
;   WAIT_BAR(2);
;     ...
;   int t=1;
;     ...
;   for(;t+5<NT;t+=2){
.LBB0_901:
	v_lshlrev_b32_e32 v16, 1, v224
	v_and_b32_e32 v244, 32, v16
	v_lshlrev_b32_e32 v16, 4, v224
	v_and_b32_e32 v16, 0xc0, v16
	v_lshl_or_b32 v225, v238, 8, v16
	v_add_u32_e32 v16, 0, v244
	v_add3_u32 v250, v16, v241, v225
	v_max3_f32 v16, v48, v49, v32
	v_max3_f32 v17, v50, v51, v33
	s_and_b32 s10, s93, 0x3fffffc0
	v_max3_f32 v16, v16, v34, v35
	v_max3_f32 v17, v17, v54, v55
	s_lshl_b32 s10, s10, 2
	v_max3_f32 v16, v16, v52, v53
	v_max3_f32 v17, v17, v38, v39
	s_add_i32 s63, s10, 0
	v_max3_f32 v16, v16, v36, v37
	v_max3_f32 v17, v17, v58, v59
	s_mov_b32 s10, 0xc61c4000
	v_max3_f32 v16, v16, v56, v57
	v_max3_f32 v17, v17, v42, v43
	s_addk_i32 s94, 0x100
	v_max3_f32 v16, v16, v40, v41
	v_max3_f32 v17, v17, v62, v63
	s_lshr_b32 s72, s94, 6
	v_max3_f32 v16, v16, v60, v61
	v_max3_f32 v17, v17, v46, v47
	s_cmp_lg_u32 0, -1
	v_max3_f32 v16, v16, v44, v45
	s_mov_b32 s18, 1
	v_max_f32_e32 v16, v16, v17
	s_mov_b32 s14, 0
	v_mov_b32_e32 v17, v16
	s_nop 1
	v_permlane32_swap_b32_e32 v16, v17
	v_max_f32_e32 v16, v16, v17
	v_lshlrev_b32_e32 v251, 4, v238
	v_cmp_ngt_f32_e32 vcc, s10, v16
	s_mov_b64 s[10:11], 0x270000
	v_lshl_add_u32 v245, v237, 2, s63
	v_cndmask_b32_e32 v16, 0, v16, vcc
	v_add_f32_e32 v247, v223, v16
	v_sub_f32_e32 v17, v48, v16
	v_sub_f32_e32 v18, v32, v16
	v_sub_f32_e32 v19, v49, v16
	v_sub_f32_e32 v20, v33, v16
	v_sub_f32_e32 v21, v50, v16
	s_nop 0
	v_xor_b32_e32 v48, 0x80000000, v247
	v_sub_f32_e32 v22, v34, v16
	v_sub_f32_e32 v23, v51, v16
	v_sub_f32_e32 v24, v35, v16
	v_sub_f32_e32 v25, v52, v16
	v_sub_f32_e32 v26, v36, v16
	v_sub_f32_e32 v27, v53, v16
	v_sub_f32_e32 v28, v37, v16
	v_sub_f32_e32 v29, v54, v16
	v_sub_f32_e32 v30, v38, v16
	v_sub_f32_e32 v31, v55, v16
	v_sub_f32_e32 v32, v39, v16
	v_sub_f32_e32 v33, v56, v16
	v_sub_f32_e32 v34, v40, v16
	v_sub_f32_e32 v35, v57, v16
	v_sub_f32_e32 v36, v41, v16
	v_sub_f32_e32 v37, v58, v16
	v_sub_f32_e32 v38, v42, v16
	v_sub_f32_e32 v39, v59, v16
	v_sub_f32_e32 v40, v43, v16
	v_sub_f32_e32 v41, v60, v16
	v_sub_f32_e32 v42, v44, v16
	v_sub_f32_e32 v43, v61, v16
	v_sub_f32_e32 v44, v45, v16
	v_sub_f32_e32 v45, v62, v16
	v_sub_f32_e32 v64, v63, v16
	v_mov_b32_e32 v49, v48
	v_mov_b32_e32 v50, v48
	v_mov_b32_e32 v51, v48
	v_mov_b32_e32 v52, v48
	v_mov_b32_e32 v53, v48
	v_mov_b32_e32 v54, v48
	v_mov_b32_e32 v55, v48
	v_mov_b32_e32 v56, v48
	v_mov_b32_e32 v57, v48
	v_mov_b32_e32 v58, v48
	v_mov_b32_e32 v59, v48
	v_mov_b32_e32 v60, v48
	v_mov_b32_e32 v61, v48
	v_mov_b32_e32 v62, v48
	v_mov_b32_e32 v63, v48
	v_sub_f32_e32 v46, v46, v16
	v_sub_f32_e32 v16, v47, v16
	s_waitcnt vmcnt(0) lgkmcnt(0)
	s_barrier
	v_exp_f32_e32 v96, v17
	v_exp_f32_e32 v79, v16
	v_lshl_add_u64 v[16:17], v[80:81], 0, s[10:11]
	s_mov_b32 s10, m0
	s_mov_b32 m0, s91
	s_nop 0
	global_load_lds_dwordx4 v[16:17], off
	s_mov_b32 m0, s10
	s_cselect_b32 s10, 0, 0
	s_add_i32 s10, s10, s24
	v_lshl_add_u64 v[16:17], v[82:83], 0, s[34:35]
	s_add_i32 s10, s10, 0x8000
	s_mov_b32 s11, m0
	s_mov_b32 m0, s10
	s_nop 0
	global_load_lds_dwordx4 v[16:17], off
	s_mov_b32 m0, s11
	ds_read_b128 v[204:207], v248 offset:8192
	ds_read_b128 v[200:203], v248 offset:8704
	ds_read_b128 v[196:199], v248 offset:10240
	ds_read_b128 v[192:195], v248 offset:10752
	ds_read_b128 v[188:191], v248 offset:12288
	ds_read_b128 v[184:187], v248 offset:12800
	ds_read_b128 v[180:183], v248 offset:14336
	ds_read_b128 v[176:179], v248 offset:14848
	v_exp_f32_e32 v97, v19
	v_exp_f32_e32 v98, v21
	v_exp_f32_e32 v99, v23
	v_exp_f32_e32 v100, v25
	v_exp_f32_e32 v101, v27
	v_exp_f32_e32 v102, v29
	v_exp_f32_e32 v103, v31
	v_exp_f32_e32 v104, v33
	v_exp_f32_e32 v105, v35
	v_exp_f32_e32 v106, v37
	v_exp_f32_e32 v107, v39
	v_exp_f32_e32 v108, v41
	v_exp_f32_e32 v109, v43
	v_exp_f32_e32 v110, v45
	v_exp_f32_e32 v111, v64
	v_exp_f32_e32 v64, v18
	v_exp_f32_e32 v65, v20
	v_exp_f32_e32 v66, v22
	v_exp_f32_e32 v67, v24
	v_exp_f32_e32 v68, v26
	v_exp_f32_e32 v69, v28
	v_exp_f32_e32 v70, v30
	v_exp_f32_e32 v71, v32
	v_exp_f32_e32 v72, v34
	v_exp_f32_e32 v73, v36
	v_exp_f32_e32 v74, v38
	v_exp_f32_e32 v75, v40
	v_exp_f32_e32 v76, v42
	v_exp_f32_e32 v77, v44
	v_exp_f32_e32 v78, v46
	s_waitcnt vmcnt(2) lgkmcnt(0)
	s_barrier
	s_andn2_b64 vcc, exec, s[8:9]
	v_cmp_gt_u32_e64 s[8:9], 32, v239
	s_mul_hi_i32 s15, s70, 0x1a00000
	s_mul_i32 s16, s70, 0x1a00000
	v_and_b32_e32 v228, 3, v224
	s_cbranch_vccnz .LBB0_972
	s_and_b32 s10, s64, 15
	s_lshl_b32 s24, s10, 7
	s_lshl_b64 s[10:11], s[68:69], 1
	s_add_u32 s10, s10, s16
	v_lshlrev_b32_e32 v16, 4, v228
	v_mov_b32_e32 v17, v223
	s_addc_u32 s11, s11, s15
	v_lshl_add_u64 v[16:17], s[10:11], 0, v[16:17]
	s_lshl_b64 s[10:11], s[66:67], 1
	s_add_u32 s10, s16, s10
	v_mov_b32_e32 v213, v223
	s_addc_u32 s11, s15, s11
	v_lshl_add_u64 v[16:17], v[16:17], 0, v[212:213]
	s_add_u32 s10, s20, s10
	v_mov_b32_e32 v30, v223
	v_mov_b32_e32 v31, v223
	v_lshl_add_u64 v[214:215], s[20:21], 0, v[16:17]
	s_addc_u32 s11, s21, s11
	v_mov_b32_e32 v16, v223
	v_mov_b32_e32 v17, v223
	v_mov_b32_e32 v18, v223
	v_mov_b32_e32 v19, v223
	v_mov_b32_e32 v20, v223
	v_mov_b32_e32 v21, v223
	v_mov_b32_e32 v22, v223
	v_mov_b32_e32 v23, v223
	v_mov_b32_e32 v24, v223
	v_mov_b32_e32 v25, v223
	v_mov_b32_e32 v26, v223
	v_mov_b32_e32 v27, v223
	v_mov_b32_e32 v28, v223
	v_mov_b32_e32 v29, v223
	v_mov_b64_e32 v[46:47], v[30:31]
	v_lshl_add_u64 v[216:217], s[10:11], 0, v[222:223]
	s_mov_b32 s11, 0
	s_movk_i32 s14, 0x4000
	s_movk_i32 s18, 0x2000
	v_mov_b32_e32 v80, 0
	s_mov_b32 s17, 6
	v_mov_b64_e32 v[44:45], v[28:29]
	v_mov_b64_e32 v[42:43], v[26:27]
	v_mov_b64_e32 v[40:41], v[24:25]
	v_mov_b64_e32 v[38:39], v[22:23]
	v_mov_b64_e32 v[36:37], v[20:21]
	v_mov_b64_e32 v[34:35], v[18:19]
	v_mov_b64_e32 v[32:33], v[16:17]
	s_mov_b32 s98, -1
.LBB0_903:
	s_add_i32 s10, s17, -5
	s_lshr_b32 s99, s10, 2
	s_cmp_lg_u32 s99, s98
	s_cbranch_scc1 .Lmoba_cupd1
.Lmoba_cret1:
	v_add_u32_e32 v81, s11, v250
	ds_read_b64_tr_b16 v[208:209], v81 offset:24576
	ds_read_b64_tr_b16 v[210:211], v81 offset:25088
	v_add_f32_e32 v82, v96, v97
	v_add_f32_e32 v82, v98, v82
	v_add_f32_e32 v82, v99, v82
	v_add_f32_e32 v82, v100, v82
	v_add_f32_e32 v82, v101, v82
	v_cvt_pk_bf16_f32 v172, v96, v97
	v_cvt_pk_bf16_f32 v173, v98, v99
	s_waitcnt lgkmcnt(9)
	v_mfma_f32_32x32x16_bf16 v[112:127], v[204:207], v[156:159], v[48:63]
	ds_read_b64_tr_b16 v[136:137], v81 offset:28672
	ds_read_b64_tr_b16 v[138:139], v81 offset:29184
	v_add_f32_e32 v82, v102, v82
	v_add_f32_e32 v82, v103, v82
	v_add_f32_e32 v82, v104, v82
	v_add_f32_e32 v98, v105, v82
	s_waitcnt lgkmcnt(10)
	v_mfma_f32_32x32x16_bf16 v[82:97], v[200:203], v[156:159], v[48:63]
	v_cvt_pk_bf16_f32 v174, v100, v101
	v_cvt_pk_bf16_f32 v175, v102, v103
	ds_read_b64_tr_b16 v[128:129], v81 offset:25600
	ds_read_b64_tr_b16 v[130:131], v81 offset:26112
	v_add_f32_e32 v98, v106, v98
	v_add_f32_e32 v98, v107, v98
	v_add_f32_e32 v98, v108, v98
	v_add_f32_e32 v98, v109, v98
	v_cvt_pk_bf16_f32 v168, v104, v105
	v_cvt_pk_bf16_f32 v169, v106, v107
	s_waitcnt lgkmcnt(11)
	v_mfma_f32_32x32x16_bf16 v[112:127], v[196:199], v[152:155], v[112:127]
	ds_read_b64_tr_b16 v[132:133], v81 offset:29696
	ds_read_b64_tr_b16 v[134:135], v81 offset:30208
	s_waitcnt lgkmcnt(12)
	v_mfma_f32_32x32x16_bf16 v[82:97], v[192:195], v[152:155], v[82:97]
	v_add_f32_e32 v98, v110, v98
	v_add_f32_e32 v98, v111, v98
	v_add_f32_e32 v98, v64, v98
	v_add_f32_e32 v98, v65, v98
	v_cvt_pk_bf16_f32 v170, v108, v109
	v_cvt_pk_bf16_f32 v171, v110, v111
	ds_read_b64_tr_b16 v[140:141], v81 offset:26624
	ds_read_b64_tr_b16 v[142:143], v81 offset:27136
	v_add_f32_e32 v98, v66, v98
	v_add_f32_e32 v98, v67, v98
	v_add_f32_e32 v98, v68, v98
	v_add_f32_e32 v102, v69, v98
	v_cvt_pk_bf16_f32 v164, v64, v65
	v_cvt_pk_bf16_f32 v165, v66, v67
	s_waitcnt lgkmcnt(13)
	v_mfma_f32_32x32x16_bf16 v[112:127], v[188:191], v[148:151], v[112:127]
	ds_read_b64_tr_b16 v[98:99], v81 offset:30720
	ds_read_b64_tr_b16 v[100:101], v81 offset:31232
	s_waitcnt lgkmcnt(14)
	v_mfma_f32_32x32x16_bf16 v[82:97], v[184:187], v[148:151], v[82:97]
	v_add_f32_e32 v64, v70, v102
	v_add_f32_e32 v64, v71, v64
	v_add_f32_e32 v64, v72, v64
	v_add_f32_e32 v64, v73, v64
	v_cvt_pk_bf16_f32 v166, v68, v69
	v_cvt_pk_bf16_f32 v167, v70, v71
	ds_read_b64_tr_b16 v[102:103], v81 offset:27648
	ds_read_b64_tr_b16 v[104:105], v81 offset:28160
	v_add_f32_e32 v64, v74, v64
	v_add_f32_e32 v64, v75, v64
	v_add_f32_e32 v64, v76, v64
	v_add_f32_e32 v64, v77, v64
	v_cvt_pk_bf16_f32 v160, v72, v73
	v_cvt_pk_bf16_f32 v161, v74, v75
	s_waitcnt lgkmcnt(14)
	v_mfma_f32_32x32x16_bf16 v[112:127], v[180:183], v[144:147], v[112:127]
	ds_read_b64_tr_b16 v[106:107], v81 offset:31744
	ds_read_b64_tr_b16 v[108:109], v81 offset:32256
	v_mfma_f32_32x32x16_bf16 v[82:97], v[176:179], v[144:147], v[82:97]
	v_add_f32_e32 v64, v78, v64
	v_add_f32_e32 v64, v79, v64
	v_add_f32_e32 v111, 0, v64
	v_cvt_pk_bf16_f32 v162, v76, v77
	v_cvt_pk_bf16_f32 v163, v78, v79
	v_lshl_add_u64 v[218:219], v[216:217], 0, s[24:25]
	v_lshl_add_u64 v[64:65], v[218:219], 0, s[54:55]
	v_lshl_add_u64 v[226:227], v[214:215], 0, s[24:25]
	s_add_i32 s11, s18, s91
	s_mov_b32 s12, m0
	s_mov_b32 m0, s11
	s_nop 0
	global_load_lds_dwordx4 v[64:65], off
	s_mov_b32 m0, s12
	v_lshl_add_u64 v[64:65], v[226:227], 0, s[56:57]
	s_add_i32 s11, s14, s71
	s_mov_b32 s12, m0
	s_mov_b32 m0, s11
	s_nop 0
	global_load_lds_dwordx4 v[64:65], off
	s_mov_b32 m0, s12
	v_add_f32_e32 v213, v80, v111
	v_max_f32_e32 v110, v113, v113
	v_max_f32_e32 v111, v112, v112
	v_max_f32_e32 v110, v111, v110
	v_max3_f32 v111, v114, v115, v83
	v_max3_f32 v110, v110, v82, v84
	v_max3_f32 v110, v110, v85, v116
	v_max3_f32 v111, v111, v118, v119
	v_max3_f32 v110, v110, v117, v86
	v_max3_f32 v111, v111, v88, v89
	v_max3_f32 v110, v110, v87, v120
	v_max3_f32 v111, v111, v122, v123
	v_max3_f32 v110, v110, v121, v90
	v_max3_f32 v111, v111, v92, v93
	v_max3_f32 v110, v110, v91, v124
	v_max3_f32 v111, v111, v126, v127
	v_max3_f32 v110, v110, v125, v94
	v_max3_f32 v111, v111, v96, v97
	v_max3_f32 v80, v110, v95, v111
	v_mov_b32_e32 v110, v80
	s_nop 1
	v_permlane32_swap_b32_e32 v80, v110
	v_max_f32_e32 v110, v110, v110
	v_max_f32_e32 v80, v80, v80
	v_max_f32_e32 v80, v80, v110
	v_cmp_lt_f32_e32 vcc, s0, v80
	s_cmp_lg_u64 vcc, 0
	s_cselect_b64 s[10:11], -1, 0
	s_cbranch_vccnz .LBB0_911
; #define WAIT_BAR(N) asm volatile("s_waitcnt vmcnt(" #N ") lgkmcnt(0)\n\ts_barrier":::"memory")
;   #define RESC() do{ if(resc){ asm volatile("s_waitcnt lgkmcnt(0)":::"memory"); \
;       _Pragma("unroll") for(int d_=0;d_<2;++d_) _Pragma("unroll") for(int r=0;r<16;++r)o[d_][r]*=wsf[crow(r,hi)]; } }while(0)
;   #define ROT() do{sl_prev=sl_cur;sl_cur=sl_next;sl_next=(sl_next==(NSLOT-1)*SLOTB)?0:sl_next+SLOTB;}while(0)
; template<int THRL,int MODE,int DM,bool DRY=false> __device__ __forceinline__ void attn_unit(int b,int h,int qb,const bf16*Q,const bf16*__restrict__ K,const bf16*__restrict__ V,bf16*O,const bf16*__restrict__ Z,const float*__restrict__ XP,const int*__restrict__ TS,volatile unsigned*lw,unsigned nxt,cha ...
;     ...
;   int t=1;
;     ...
;   for(;t+5<NT;t+=2){
;     STEP(pB0,pB1,pA0,pA1,t,true,true,true);     WAIT_BAR(2); RESC(); ROT();
.LBB0_904:
	s_waitcnt lgkmcnt(14)
	v_mfma_f32_32x32x16_bf16 v[16:31], v[172:175], v[208:211], v[16:31]
	v_exp_f32_e32 v64, v82
	v_exp_f32_e32 v65, v83
	v_exp_f32_e32 v80, v112
	v_exp_f32_e32 v81, v113
	s_waitcnt lgkmcnt(12)
	v_mfma_f32_32x32x16_bf16 v[32:47], v[172:175], v[136:139], v[32:47]
	v_exp_f32_e32 v82, v114
	v_exp_f32_e32 v83, v115
	v_exp_f32_e32 v66, v84
	v_exp_f32_e32 v67, v85
	v_add_u32_e32 v255, s14, v248
	ds_read_b128 v[112:115], v255
	ds_read_b128 v[200:203], v255 offset:512
	s_waitcnt lgkmcnt(12)
	v_mfma_f32_32x32x16_bf16 v[16:31], v[168:171], v[128:131], v[16:31]
	v_exp_f32_e32 v68, v86
	v_exp_f32_e32 v69, v87
	v_exp_f32_e32 v70, v88
	v_exp_f32_e32 v71, v89
	ds_read_b128 v[204:207], v255 offset:2048
	ds_read_b128 v[196:199], v255 offset:2560
	s_waitcnt lgkmcnt(12)
	v_mfma_f32_32x32x16_bf16 v[32:47], v[168:171], v[132:135], v[32:47]
	v_exp_f32_e32 v72, v90
	v_exp_f32_e32 v73, v91
	v_exp_f32_e32 v74, v92
	v_exp_f32_e32 v75, v93
	ds_read_b128 v[192:195], v255 offset:4096
	ds_read_b128 v[184:187], v255 offset:4608
	s_waitcnt lgkmcnt(12)
	v_mfma_f32_32x32x16_bf16 v[16:31], v[164:167], v[140:143], v[16:31]
	v_exp_f32_e32 v76, v94
	v_exp_f32_e32 v77, v95
	v_exp_f32_e32 v78, v96
	v_exp_f32_e32 v79, v97
	ds_read_b128 v[188:191], v255 offset:6144
	ds_read_b128 v[180:183], v255 offset:6656
	s_waitcnt lgkmcnt(12)
	v_mfma_f32_32x32x16_bf16 v[32:47], v[164:167], v[98:101], v[32:47]
	v_exp_f32_e32 v84, v116
	v_exp_f32_e32 v85, v117
	v_exp_f32_e32 v86, v118
	v_exp_f32_e32 v87, v119
	s_waitcnt lgkmcnt(10)
	v_mfma_f32_32x32x16_bf16 v[16:31], v[160:163], v[102:105], v[16:31]
	v_exp_f32_e32 v88, v120
	v_exp_f32_e32 v89, v121
	v_exp_f32_e32 v90, v122
	v_exp_f32_e32 v91, v123
	s_waitcnt lgkmcnt(8)
	v_mfma_f32_32x32x16_bf16 v[32:47], v[160:163], v[106:109], v[32:47]
	v_exp_f32_e32 v92, v124
	v_exp_f32_e32 v93, v125
	v_exp_f32_e32 v94, v126
	v_exp_f32_e32 v95, v127
	s_waitcnt vmcnt(2) lgkmcnt(0)
	s_barrier
	s_andn2_b64 vcc, exec, s[10:11]
	v_add_u32_e32 v208, s63, v251
	s_cbranch_vccnz .LBB0_906
	s_waitcnt lgkmcnt(0)
	ds_read_b128 v[96:99], v208 offset:49248
	ds_read_b128 v[100:103], v208 offset:49216
	ds_read_b128 v[104:107], v208 offset:49184
	ds_read_b128 v[108:111], v208 offset:49152
	s_waitcnt lgkmcnt(3)
	v_pk_mul_f32 v[28:29], v[28:29], v[96:97]
	s_waitcnt lgkmcnt(2)
	v_pk_mul_f32 v[24:25], v[24:25], v[100:101]
	s_waitcnt lgkmcnt(1)
	v_pk_mul_f32 v[20:21], v[20:21], v[104:105]
	v_pk_mul_f32 v[30:31], v[30:31], v[98:99]
	v_pk_mul_f32 v[26:27], v[26:27], v[102:103]
	v_pk_mul_f32 v[22:23], v[22:23], v[106:107]
	s_waitcnt lgkmcnt(0)
	v_pk_mul_f32 v[18:19], v[18:19], v[110:111]
	v_pk_mul_f32 v[16:17], v[16:17], v[108:109]
	v_pk_mul_f32 v[44:45], v[44:45], v[96:97]
	v_pk_mul_f32 v[40:41], v[40:41], v[100:101]
	v_pk_mul_f32 v[36:37], v[36:37], v[104:105]
	v_pk_mul_f32 v[46:47], v[46:47], v[98:99]
	v_pk_mul_f32 v[42:43], v[42:43], v[102:103]
	v_pk_mul_f32 v[38:39], v[38:39], v[106:107]
	v_pk_mul_f32 v[34:35], v[34:35], v[110:111]
	v_pk_mul_f32 v[32:33], v[32:33], v[108:109]
.LBB0_906:
	s_add_i32 s10, s17, -4
	s_add_i32 s11, s14, 0x2000
	s_cmpk_lg_i32 s14, 0x4000
	s_cselect_b32 s70, s11, 0
	s_lshr_b32 s99, s10, 2
	s_cmp_lg_u32 s99, s98
	s_cbranch_scc1 .Lmoba_cupd2
.Lmoba_cret2:
	v_add_u32_e32 v209, s18, v250
	ds_read_b64_tr_b16 v[176:177], v209 offset:24576
	ds_read_b64_tr_b16 v[178:179], v209 offset:25088
	v_add_f32_e32 v96, v80, v81
	v_add_f32_e32 v96, v82, v96
	v_add_f32_e32 v96, v83, v96
	v_add_f32_e32 v96, v84, v96
	v_add_f32_e32 v116, v85, v96
	s_waitcnt lgkmcnt(9)
	v_mfma_f32_32x32x16_bf16 v[96:111], v[112:115], v[156:159], v[48:63]
	v_cvt_pk_bf16_f32 v172, v80, v81
	v_cvt_pk_bf16_f32 v173, v82, v83
	ds_read_b64_tr_b16 v[136:137], v209 offset:28672
	ds_read_b64_tr_b16 v[138:139], v209 offset:29184
	v_add_f32_e32 v80, v86, v116
	v_add_f32_e32 v80, v87, v80
	v_add_f32_e32 v80, v88, v80
	v_add_f32_e32 v80, v89, v80
	v_cvt_pk_bf16_f32 v174, v84, v85
	v_cvt_pk_bf16_f32 v175, v86, v87
	s_waitcnt lgkmcnt(10)
	v_mfma_f32_32x32x16_bf16 v[112:127], v[200:203], v[156:159], v[48:63]
	ds_read_b64_tr_b16 v[128:129], v209 offset:25600
	ds_read_b64_tr_b16 v[130:131], v209 offset:26112
	s_waitcnt lgkmcnt(11)
	v_mfma_f32_32x32x16_bf16 v[96:111], v[204:207], v[152:155], v[96:111]
	v_add_f32_e32 v80, v90, v80
	v_add_f32_e32 v80, v91, v80
	v_add_f32_e32 v80, v92, v80
	v_add_f32_e32 v80, v93, v80
	v_cvt_pk_bf16_f32 v168, v88, v89
	v_cvt_pk_bf16_f32 v169, v90, v91
	ds_read_b64_tr_b16 v[132:133], v209 offset:29696
	ds_read_b64_tr_b16 v[134:135], v209 offset:30208
	v_add_f32_e32 v80, v94, v80
	v_add_f32_e32 v80, v95, v80
	v_add_f32_e32 v80, v64, v80
	v_add_f32_e32 v80, v65, v80
	v_cvt_pk_bf16_f32 v170, v92, v93
	v_cvt_pk_bf16_f32 v171, v94, v95
	s_waitcnt lgkmcnt(12)
	v_mfma_f32_32x32x16_bf16 v[112:127], v[196:199], v[152:155], v[112:127]
	ds_read_b64_tr_b16 v[140:141], v209 offset:26624
	ds_read_b64_tr_b16 v[142:143], v209 offset:27136
	s_waitcnt lgkmcnt(13)
	v_mfma_f32_32x32x16_bf16 v[96:111], v[192:195], v[148:151], v[96:111]
	v_add_f32_e32 v80, v66, v80
	v_add_f32_e32 v80, v67, v80
	v_add_f32_e32 v80, v68, v80
	v_add_f32_e32 v80, v69, v80
	v_cvt_pk_bf16_f32 v164, v64, v65
	v_cvt_pk_bf16_f32 v165, v66, v67
	ds_read_b64_tr_b16 v[82:83], v209 offset:30720
	ds_read_b64_tr_b16 v[84:85], v209 offset:31232
	v_add_f32_e32 v64, v70, v80
	v_add_f32_e32 v64, v71, v64
	v_add_f32_e32 v64, v72, v64
	v_add_f32_e32 v64, v73, v64
	v_cvt_pk_bf16_f32 v166, v68, v69
	v_cvt_pk_bf16_f32 v167, v70, v71
	s_waitcnt lgkmcnt(14)
; #define WAIT_BAR(N) asm volatile("s_waitcnt vmcnt(" #N ") lgkmcnt(0)\n\ts_barrier":::"memory")
;   #define RESC() do{ if(resc){ asm volatile("s_waitcnt lgkmcnt(0)":::"memory"); \
;       _Pragma("unroll") for(int d_=0;d_<2;++d_) _Pragma("unroll") for(int r=0;r<16;++r)o[d_][r]*=wsf[crow(r,hi)]; } }while(0)
;   #define ROT() do{sl_prev=sl_cur;sl_cur=sl_next;sl_next=(sl_next==(NSLOT-1)*SLOTB)?0:sl_next+SLOTB;}while(0)
; template<int THRL,int MODE,int DM,bool DRY=false> __device__ __forceinline__ void attn_unit(int b,int h,int qb,const bf16*Q,const bf16*__restrict__ K,const bf16*__restrict__ V,bf16*O,const bf16*__restrict__ Z,const float*__restrict__ XP,const int*__restrict__ TS,volatile unsigned*lw,unsigned nxt,cha ...
;     ...
;   int t=1;
;     ...
;   for(;t+5<NT;t+=2){
;     STEP(pB0,pB1,pA0,pA1,t,true,true,true);     WAIT_BAR(2); RESC(); ROT();
	v_mfma_f32_32x32x16_bf16 v[112:127], v[184:187], v[148:151], v[112:127]
	ds_read_b64_tr_b16 v[86:87], v209 offset:27648
	ds_read_b64_tr_b16 v[88:89], v209 offset:28160
	s_waitcnt lgkmcnt(14)
	v_mfma_f32_32x32x16_bf16 v[96:111], v[188:191], v[144:147], v[96:111]
	v_add_f32_e32 v64, v74, v64
	v_add_f32_e32 v64, v75, v64
	v_add_f32_e32 v64, v76, v64
	v_add_f32_e32 v64, v77, v64
	v_cvt_pk_bf16_f32 v160, v72, v73
	v_cvt_pk_bf16_f32 v161, v74, v75
	ds_read_b64_tr_b16 v[90:91], v209 offset:31744
	ds_read_b64_tr_b16 v[92:93], v209 offset:32256
	v_add_f32_e32 v64, v78, v64
	v_add_f32_e32 v64, v79, v64
	v_add_f32_e32 v80, 0, v64
	v_cvt_pk_bf16_f32 v162, v76, v77
	v_cvt_pk_bf16_f32 v163, v78, v79
	v_mfma_f32_32x32x16_bf16 v[112:127], v[180:183], v[144:147], v[112:127]
	s_mov_b64 s[12:13], 0x1f12400
	v_lshl_add_u64 v[64:65], v[218:219], 0, s[12:13]
	s_add_i32 s11, s14, s91
	s_mov_b32 s12, m0
	s_mov_b32 m0, s11
	s_nop 0
	global_load_lds_dwordx4 v[64:65], off
	s_mov_b32 m0, s12
	s_mov_b64 s[12:13], 0x1d72c00
	v_lshl_add_u64 v[64:65], v[226:227], 0, s[12:13]
	s_add_i32 s11, s70, s71
	s_mov_b32 s12, m0
	s_mov_b32 m0, s11
	s_nop 0
	global_load_lds_dwordx4 v[64:65], off
	s_mov_b32 m0, s12
	v_add_f32_e32 v80, v213, v80
	v_max_f32_e32 v81, v97, v97
	v_max_f32_e32 v94, v96, v96
	v_max_f32_e32 v81, v94, v81
	v_max3_f32 v94, v98, v99, v113
	v_max3_f32 v81, v81, v112, v114
	v_max3_f32 v81, v81, v115, v100
	v_max3_f32 v94, v94, v102, v103
	v_max3_f32 v81, v81, v101, v116
	v_max3_f32 v94, v94, v118, v119
	v_max3_f32 v81, v81, v117, v104
	v_max3_f32 v94, v94, v106, v107
	v_max3_f32 v81, v81, v105, v120
	v_max3_f32 v94, v94, v122, v123
	v_max3_f32 v81, v81, v121, v108
	v_max3_f32 v94, v94, v110, v111
	v_max3_f32 v81, v81, v109, v124
	v_max3_f32 v94, v94, v126, v127
	v_max3_f32 v81, v81, v125, v94
	v_mov_b32_e32 v94, v81
	s_nop 1
	v_permlane32_swap_b32_e32 v81, v94
	v_max_f32_e32 v94, v94, v94
	v_max_f32_e32 v81, v81, v81
	v_max_f32_e32 v81, v81, v94
	v_cmp_lt_f32_e32 vcc, s0, v81
	s_cmp_lg_u64 vcc, 0
	s_cselect_b64 s[10:11], -1, 0
	s_cbranch_vccnz .LBB0_914
.LBB0_907:
	s_waitcnt lgkmcnt(14)
	v_mfma_f32_32x32x16_bf16 v[16:31], v[172:175], v[176:179], v[16:31]
	v_exp_f32_e32 v96, v96
	v_exp_f32_e32 v97, v97
	v_exp_f32_e32 v98, v98
	v_exp_f32_e32 v99, v99
	s_waitcnt lgkmcnt(12)
	v_mfma_f32_32x32x16_bf16 v[32:47], v[172:175], v[136:139], v[32:47]
	v_exp_f32_e32 v100, v100
	v_exp_f32_e32 v101, v101
	v_exp_f32_e32 v102, v102
	v_exp_f32_e32 v103, v103
	v_add_u32_e32 v81, s70, v248
	ds_read_b128 v[204:207], v81
	ds_read_b128 v[200:203], v81 offset:512
	s_waitcnt lgkmcnt(12)
	v_mfma_f32_32x32x16_bf16 v[16:31], v[168:171], v[128:131], v[16:31]
	v_exp_f32_e32 v104, v104
	v_exp_f32_e32 v105, v105
	v_exp_f32_e32 v106, v106
	v_exp_f32_e32 v107, v107
	ds_read_b128 v[196:199], v81 offset:2048
	ds_read_b128 v[192:195], v81 offset:2560
	s_waitcnt lgkmcnt(12)
	v_mfma_f32_32x32x16_bf16 v[32:47], v[168:171], v[132:135], v[32:47]
	v_exp_f32_e32 v108, v108
	v_exp_f32_e32 v109, v109
	v_exp_f32_e32 v110, v110
	v_exp_f32_e32 v111, v111
	ds_read_b128 v[188:191], v81 offset:4096
	ds_read_b128 v[184:187], v81 offset:4608
	s_waitcnt lgkmcnt(12)
	v_mfma_f32_32x32x16_bf16 v[16:31], v[164:167], v[140:143], v[16:31]
	v_exp_f32_e32 v64, v112
	v_exp_f32_e32 v65, v113
	v_exp_f32_e32 v66, v114
	v_exp_f32_e32 v67, v115
	ds_read_b128 v[180:183], v81 offset:6144
	ds_read_b128 v[176:179], v81 offset:6656
	s_waitcnt lgkmcnt(12)
	v_mfma_f32_32x32x16_bf16 v[32:47], v[164:167], v[82:85], v[32:47]
	v_exp_f32_e32 v68, v116
	v_exp_f32_e32 v69, v117
	v_exp_f32_e32 v70, v118
	v_exp_f32_e32 v71, v119
	s_waitcnt lgkmcnt(10)
	v_mfma_f32_32x32x16_bf16 v[16:31], v[160:163], v[86:89], v[16:31]
	v_exp_f32_e32 v72, v120
	v_exp_f32_e32 v73, v121
	v_exp_f32_e32 v74, v122
	v_exp_f32_e32 v75, v123
	s_waitcnt lgkmcnt(8)
	v_mfma_f32_32x32x16_bf16 v[32:47], v[160:163], v[90:93], v[32:47]
	v_exp_f32_e32 v76, v124
	v_exp_f32_e32 v77, v125
	v_exp_f32_e32 v78, v126
	v_exp_f32_e32 v79, v127
	s_waitcnt vmcnt(2) lgkmcnt(0)
	s_barrier
	s_andn2_b64 vcc, exec, s[10:11]
	s_cbranch_vccnz .LBB0_909
	s_waitcnt lgkmcnt(0)
	ds_read_b128 v[82:85], v208 offset:49248
	ds_read_b128 v[86:89], v208 offset:49216
	ds_read_b128 v[90:93], v208 offset:49184
	ds_read_b128 v[112:115], v208 offset:49152
	s_waitcnt lgkmcnt(3)
	v_pk_mul_f32 v[28:29], v[28:29], v[82:83]
	s_waitcnt lgkmcnt(2)
	v_pk_mul_f32 v[24:25], v[24:25], v[86:87]
	s_waitcnt lgkmcnt(1)
	v_pk_mul_f32 v[20:21], v[20:21], v[90:91]
	v_pk_mul_f32 v[30:31], v[30:31], v[84:85]
	v_pk_mul_f32 v[26:27], v[26:27], v[88:89]
	v_pk_mul_f32 v[22:23], v[22:23], v[92:93]
	s_waitcnt lgkmcnt(0)
	v_pk_mul_f32 v[18:19], v[18:19], v[114:115]
	v_pk_mul_f32 v[16:17], v[16:17], v[112:113]
	v_pk_mul_f32 v[44:45], v[44:45], v[82:83]
	v_pk_mul_f32 v[40:41], v[40:41], v[86:87]
	v_pk_mul_f32 v[36:37], v[36:37], v[90:91]
	v_pk_mul_f32 v[46:47], v[46:47], v[84:85]
	v_pk_mul_f32 v[42:43], v[42:43], v[88:89]
	v_pk_mul_f32 v[38:39], v[38:39], v[92:93]
	v_pk_mul_f32 v[34:35], v[34:35], v[114:115]
	v_pk_mul_f32 v[32:33], v[32:33], v[112:113]

.LBB0_911:
	v_max_f32_e32 v48, v80, v80
	v_max_f32_e32 v80, 0, v48
	v_exp_f32_e64 v110, -v80
	v_add_f32_e32 v247, v247, v80
	v_xor_b32_e32 v48, 0x80000000, v247
	v_cndmask_b32_e64 v48, v236, v48, s[100:101]
	v_mov_b32_e32 v49, v48
	v_mov_b32_e32 v50, v48
	v_mov_b32_e32 v51, v48
	v_mov_b32_e32 v52, v48
	v_mov_b32_e32 v53, v48
	v_mov_b32_e32 v54, v48
	v_mov_b32_e32 v55, v48
	v_mov_b32_e32 v56, v48
	v_mov_b32_e32 v57, v48
	v_mov_b32_e32 v58, v48
	v_mov_b32_e32 v59, v48
	v_mov_b32_e32 v60, v48
	v_mov_b32_e32 v61, v48
	v_mov_b32_e32 v62, v48
	v_mov_b32_e32 v63, v48
	s_and_saveexec_b64 s[12:13], s[8:9]
	ds_write_b32 v245, v110 offset:49152
	s_or_b64 exec, exec, s[12:13]
	v_sub_f32_e32 v112, v112, v80
	v_sub_f32_e32 v82, v82, v80
	v_sub_f32_e32 v113, v113, v80
	v_sub_f32_e32 v83, v83, v80
	v_sub_f32_e32 v114, v114, v80
	v_sub_f32_e32 v84, v84, v80
	v_sub_f32_e32 v115, v115, v80
	v_sub_f32_e32 v85, v85, v80
	v_sub_f32_e32 v116, v116, v80
	v_sub_f32_e32 v86, v86, v80
	v_sub_f32_e32 v117, v117, v80
	v_sub_f32_e32 v87, v87, v80
	v_sub_f32_e32 v118, v118, v80
	v_sub_f32_e32 v88, v88, v80
	v_sub_f32_e32 v119, v119, v80
	v_sub_f32_e32 v89, v89, v80
	v_sub_f32_e32 v120, v120, v80
	v_sub_f32_e32 v90, v90, v80
	v_sub_f32_e32 v121, v121, v80
	v_sub_f32_e32 v91, v91, v80
	v_sub_f32_e32 v122, v122, v80
	v_sub_f32_e32 v92, v92, v80
	v_sub_f32_e32 v123, v123, v80
	v_sub_f32_e32 v93, v93, v80
	v_sub_f32_e32 v124, v124, v80
	v_sub_f32_e32 v94, v94, v80
	v_sub_f32_e32 v125, v125, v80
	v_sub_f32_e32 v95, v95, v80
	v_sub_f32_e32 v126, v126, v80
	v_sub_f32_e32 v96, v96, v80
	v_sub_f32_e32 v127, v127, v80
	v_sub_f32_e32 v97, v97, v80
	v_mul_f32_e32 v213, v213, v110
	s_branch .LBB0_904
.LBB0_914:
	v_max_f32_e32 v48, v81, v81
	v_max_f32_e32 v81, 0, v48
	v_exp_f32_e64 v94, -v81
	v_add_f32_e32 v247, v247, v81
	v_xor_b32_e32 v48, 0x80000000, v247
	v_cndmask_b32_e64 v48, v236, v48, s[100:101]
	v_mov_b32_e32 v49, v48
	v_mov_b32_e32 v50, v48
	v_mov_b32_e32 v51, v48
	v_mov_b32_e32 v52, v48
	v_mov_b32_e32 v53, v48
	v_mov_b32_e32 v54, v48
	v_mov_b32_e32 v55, v48
	v_mov_b32_e32 v56, v48
	v_mov_b32_e32 v57, v48
	v_mov_b32_e32 v58, v48
	v_mov_b32_e32 v59, v48
	v_mov_b32_e32 v60, v48
	v_mov_b32_e32 v61, v48
	v_mov_b32_e32 v62, v48
	v_mov_b32_e32 v63, v48
	s_and_saveexec_b64 s[12:13], s[8:9]
	ds_write_b32 v245, v94 offset:49152
	s_or_b64 exec, exec, s[12:13]
	v_sub_f32_e32 v96, v96, v81
	v_sub_f32_e32 v112, v112, v81
	v_sub_f32_e32 v97, v97, v81
	v_sub_f32_e32 v113, v113, v81
	v_sub_f32_e32 v98, v98, v81
	v_sub_f32_e32 v114, v114, v81
	v_sub_f32_e32 v99, v99, v81
	v_sub_f32_e32 v115, v115, v81
	v_sub_f32_e32 v100, v100, v81
	v_sub_f32_e32 v116, v116, v81
	v_sub_f32_e32 v101, v101, v81
	v_sub_f32_e32 v117, v117, v81
	v_sub_f32_e32 v102, v102, v81
	v_sub_f32_e32 v118, v118, v81
	v_sub_f32_e32 v103, v103, v81
	v_sub_f32_e32 v119, v119, v81
	v_sub_f32_e32 v104, v104, v81
	v_sub_f32_e32 v120, v120, v81
	v_sub_f32_e32 v105, v105, v81
	v_sub_f32_e32 v121, v121, v81
	v_sub_f32_e32 v106, v106, v81
	v_sub_f32_e32 v122, v122, v81
	v_sub_f32_e32 v107, v107, v81
	v_sub_f32_e32 v123, v123, v81
	v_sub_f32_e32 v108, v108, v81
	v_sub_f32_e32 v124, v124, v81
	v_sub_f32_e32 v109, v109, v81
	v_sub_f32_e32 v125, v125, v81
	v_sub_f32_e32 v110, v110, v81
	v_sub_f32_e32 v126, v126, v81
	v_sub_f32_e32 v111, v111, v81
	v_sub_f32_e32 v127, v127, v81
	v_mul_f32_e32 v80, v80, v94
	s_branch .LBB0_907
.Lmoba_cupd1:
	s_mov_b32 s98, s99
	v_bfe_u32 v255, v249, s99, 1
	v_cmp_ne_u32_e64 s[100:101], 0, v255
	v_xor_b32_e32 v48, 0x80000000, v247
	s_nop 1
	v_cndmask_b32_e64 v48, v236, v48, s[100:101]
	v_mov_b32_e32 v49, v48
	v_mov_b32_e32 v50, v48
	v_mov_b32_e32 v51, v48
	v_mov_b32_e32 v52, v48
	v_mov_b32_e32 v53, v48
	v_mov_b32_e32 v54, v48
	v_mov_b32_e32 v55, v48
	v_mov_b32_e32 v56, v48
	v_mov_b32_e32 v57, v48
	v_mov_b32_e32 v58, v48
	v_mov_b32_e32 v59, v48
	v_mov_b32_e32 v60, v48
	v_mov_b32_e32 v61, v48
	v_mov_b32_e32 v62, v48
	v_mov_b32_e32 v63, v48
	s_branch .Lmoba_cret1

; #define WAIT_BAR(N) asm volatile("s_waitcnt vmcnt(" #N ") lgkmcnt(0)\n\ts_barrier":::"memory")
;   #define RESC() do{ if(resc){ asm volatile("s_waitcnt lgkmcnt(0)":::"memory"); \
;       _Pragma("unroll") for(int d_=0;d_<2;++d_) _Pragma("unroll") for(int r=0;r<16;++r)o[d_][r]*=wsf[crow(r,hi)]; } }while(0)
;   #define ROT() do{sl_prev=sl_cur;sl_cur=sl_next;sl_next=(sl_next==(NSLOT-1)*SLOTB)?0:sl_next+SLOTB;}while(0)
; template<int THRL,int MODE,int DM,bool DRY=false> __device__ __forceinline__ void attn_unit(int b,int h,int qb,const bf16*Q,const bf16*__restrict__ K,const bf16*__restrict__ V,bf16*O,const bf16*__restrict__ Z,const float*__restrict__ XP,const int*__restrict__ TS,volatile unsigned*lw,unsigned nxt,cha ...
;     ...
;   for(;t+5<NT;t+=2){
;     STEP(pB0,pB1,pA0,pA1,t,true,true,true);     WAIT_BAR(2); RESC(); ROT();
;     STEP(pA0,pA1,pB0,pB1,t+1,true,true,true);   WAIT_BAR(2); RESC(); ROT();
;   }
;     ...
;   for(;t+1<NT;t+=2){
.LBB0_917:
	v_xor_b32_e32 v48, 0x80000000, v247
	v_mov_b32_e32 v49, v48
	v_mov_b32_e32 v50, v48
	v_mov_b32_e32 v51, v48
	v_mov_b32_e32 v52, v48
	v_mov_b32_e32 v53, v48
	v_mov_b32_e32 v54, v48
	v_mov_b32_e32 v55, v48
	v_mov_b32_e32 v56, v48
	v_mov_b32_e32 v57, v48
	v_mov_b32_e32 v58, v48
	v_mov_b32_e32 v59, v48
	v_mov_b32_e32 v60, v48
	v_mov_b32_e32 v61, v48
	v_mov_b32_e32 v62, v48
	v_mov_b32_e32 v63, v48
	s_add_i32 s18, s17, -3
	s_add_i32 s8, s18, 1
	s_cmp_ge_u32 s8, s72
	s_cbranch_scc1 .LBB0_973
